# GEMM phase entry: lagging wave group's last prologue barrier deferred (same flag as the per-tile late stagger barrier) until after scheduling code + accumulator zeroing
# speedup vs baseline: 1.0081x; 1.0081x over previous
.LBB0_325:
	s_add_u32 s10, s90, 0xdd00000
	s_addc_u32 s11, s91, 0
	s_add_u32 s12, s90, 0x1b400000
	s_mov_b64 s[14:15], 0x80
	s_addc_u32 s13, s91, 0
	s_add_i32 m0, s7, 0x18000
	v_lshl_add_u64 v[6:7], v[6:7], 0, s[14:15]
	s_and_b32 s3, s3, 3
	s_lshl_b32 s5, s2, 13
	s_waitcnt vmcnt(2)
	s_barrier
	global_load_lds_dwordx4 v[6:7], off
	v_lshl_add_u64 v[4:5], v[4:5], 0, s[14:15]
	s_add_i32 m0, s7, 0x1a000
	s_add_i32 s43, s7, 0x8000
	s_add_i32 s44, s7, 0xa000
	global_load_lds_dwordx4 v[4:5], off
	v_lshl_add_u64 v[0:1], v[0:1], 0, s[14:15]
	s_mov_b32 m0, s43
	s_add_u32 s18, s28, 0x40080
	global_load_lds_dwordx4 v[0:1], off
	v_lshl_add_u64 v[0:1], v[2:3], 0, s[14:15]
	s_mov_b32 m0, s44
	s_addc_u32 s19, s29, 0
	global_load_lds_dwordx4 v[0:1], off
	s_add_i32 m0, s7, 0x1c000
	v_lshl_add_u64 v[0:1], s[18:19], 0, v[140:141]
	global_load_lds_dwordx4 v[0:1], off
	v_lshl_add_u64 v[0:1], s[18:19], 0, v[142:143]
	s_add_i32 m0, s7, 0x1e000
	v_lshlrev_b32_e32 v2, 3, v165
	global_load_lds_dwordx4 v[0:1], off
	v_lshlrev_b32_e32 v1, 2, v166
	v_lshl_or_b32 v0, v166, 6, v167
	v_and_b32_e32 v1, 32, v1
	v_bitop3_b32 v3, v0, s5, v1 bitop3:0xde
	v_lshlrev_b32_e32 v0, 8, v8
	v_and_b32_e32 v0, 0x200, v0
	v_and_b32_e32 v146, 8, v2
	v_lshl_or_b32 v0, s3, 10, v0
	v_lshlrev_b32_e32 v144, 5, v166
	v_or_b32_e32 v171, 0xffffa000, v0
	v_or_b32_e32 v172, 0xffffb000, v0
	v_lshl_add_u64 v[0:1], s[12:13], 0, v[144:145]
	v_lshlrev_b32_e32 v144, 1, v146
	v_lshl_add_u64 v[148:149], v[0:1], 0, v[144:145]
	v_lshlrev_b32_e32 v0, 8, v204
	v_and_b32_e32 v0, 0x38000, v0
	v_lshlrev_b32_e32 v1, 11, v163
	v_or3_b32 v0, v147, v0, v1
	v_add_u32_e32 v150, v0, v162
	v_lshlrev_b32_e32 v0, 4, v164
	s_waitcnt vmcnt(6)
	s_cmpk_lt_u32 s16, 0x100
	v_and_b32_e32 v0, 0x78000, v0
	v_lshl_or_b32 v170, s3, 12, v168
	s_cselect_b64 s[16:17], -1, 0
	v_or3_b32 v0, v147, v0, v1
	s_add_i32 s47, 0, 0x10000
	s_add_i32 s48, 0, 0x14000
	v_lshl_or_b32 v169, s2, 6, v166
	s_waitcnt lgkmcnt(0)
	s_ashr_i32 s45, s33, 31
	s_ashr_i32 s46, s80, 31
	v_lshl_or_b32 v173, s3, 5, v2
	v_mov_b32_e32 v151, v145
	v_add_u32_e32 v152, v0, v162
	v_mov_b32_e32 v153, v145
	v_mov_b64_e32 v[154:155], 0x4e6
	v_mov_b64_e32 v[156:157], 0x4e5
	v_add_u32_e32 v174, s47, v170
	v_add_u32_e32 v175, s48, v170
	v_add_u32_e32 v176, 0, v3
	s_movk_i32 s49, 0x2600
	s_movk_i32 s50, 0x7e
	s_movk_i32 s51, 0x500
	s_movk_i32 s52, 0x7f
	s_andn2_b64 vcc, exec, s[8:9]
	s_cbranch_vccnz .Lpe_bar_1
	v_writelane_b32 v255, 1, 53
	s_branch .Lpe_done_1
.Lpe_bar_1:
	s_barrier
.Lpe_done_1:
	s_branch .LBB0_328
.LBB0_326:
	s_mov_b64 s[2:3], 0

.LBB0_477:
	s_lshl_b32 s4, s4, 5
	s_lshl_b32 s13, s12, 13
	s_and_b32 s16, s4, 0x60
	s_add_u32 s4, s90, 0xa00000
	s_mov_b64 s[6:7], 0x80
	s_addc_u32 s5, s91, 0
	s_add_i32 m0, s41, 0x18000
	v_lshl_add_u64 v[6:7], v[6:7], 0, s[6:7]
	s_waitcnt vmcnt(2)
	s_barrier
	global_load_lds_dwordx4 v[6:7], off
	v_lshl_add_u64 v[4:5], v[4:5], 0, s[6:7]
	s_add_i32 m0, s41, 0x1a000
	s_add_i32 s46, s41, 0x8000
	s_add_i32 s47, s41, 0xa000
	global_load_lds_dwordx4 v[4:5], off
	v_lshl_add_u64 v[0:1], v[0:1], 0, s[6:7]
	s_mov_b32 m0, s46
	s_add_u32 s14, s28, 0x40080
	global_load_lds_dwordx4 v[0:1], off
	v_lshl_add_u64 v[0:1], v[2:3], 0, s[6:7]
	s_mov_b32 m0, s47
	s_addc_u32 s15, s29, 0
	global_load_lds_dwordx4 v[0:1], off
	s_add_i32 m0, s41, 0x1c000
	v_lshl_add_u64 v[0:1], s[14:15], 0, v[136:137]
	global_load_lds_dwordx4 v[0:1], off
	v_lshl_add_u64 v[0:1], s[14:15], 0, v[138:139]
	s_add_i32 m0, s41, 0x1e000
	v_lshlrev_b32_e32 v2, 11, v163
	global_load_lds_dwordx4 v[0:1], off
	v_lshlrev_b32_e32 v1, 2, v166
	v_lshl_or_b32 v0, v166, 6, v167
	v_and_b32_e32 v1, 32, v1
	v_bitop3_b32 v0, v0, s13, v1 bitop3:0xde
	v_lshlrev_b32_e32 v1, 8, v204
	v_and_b32_e32 v1, 0x38000, v1
	v_or3_b32 v1, v147, v1, v2
	v_add_u32_e32 v128, v1, v162
	v_lshlrev_b32_e32 v1, 4, v164
	s_waitcnt vmcnt(6)
	s_cmpk_lt_u32 s11, 0x100
	v_and_b32_e32 v1, 0x78000, v1
	s_sext_i32_i8 s9, s10
	v_lshl_or_b32 v133, s16, 7, v168
	s_cselect_b64 s[10:11], -1, 0
	v_or3_b32 v1, v147, v1, v2
	s_add_i32 s49, 0, 0x10000
	s_add_i32 s50, 0, 0x14000
	v_lshl_or_b32 v132, s12, 6, v166
	s_ashr_i32 s48, s33, 31
	v_lshl_or_b32 v134, v165, 2, s16
	v_mov_b32_e32 v129, v137
	v_add_u32_e32 v130, v1, v162
	v_mov_b32_e32 v131, v137
	v_add_u32_e32 v135, s49, v133
	v_add_u32_e32 v140, s50, v133
	v_add_u32_e32 v141, 0, v0
	s_mov_b32 s51, 0x90000
	s_mov_b64 s[12:13], 0xa0000
	s_mov_b32 s52, 0xa0000
	s_mov_b64 s[14:15], 0xb0000
	s_andn2_b64 vcc, exec, s[2:3]
	s_cbranch_vccnz .Lpe_bar_2
	v_writelane_b32 v255, 1, 53
	s_branch .Lpe_done_2
.Lpe_bar_2:
	s_barrier
.Lpe_done_2:
	s_branch .LBB0_480
.LBB0_478:
	s_mov_b64 s[8:9], 0

.LBB0_783:
	s_lshl_b32 s36, s14, 6
	s_lshl_b32 s18, s14, 13
	s_mov_b64 s[14:15], 0x80
	s_add_i32 m0, s30, 0x18000
	v_lshl_add_u64 v[6:7], v[6:7], 0, s[14:15]
	s_and_b32 s19, s6, 0x60
	s_waitcnt vmcnt(2)
	s_barrier
	global_load_lds_dwordx4 v[6:7], off
	v_lshl_add_u64 v[4:5], v[4:5], 0, s[14:15]
	s_add_i32 m0, s30, 0x1a000
	s_add_i32 s37, s30, 0x8000
	s_add_i32 s38, s30, 0xa000
	global_load_lds_dwordx4 v[4:5], off
	v_lshl_add_u64 v[0:1], v[0:1], 0, s[14:15]
	s_mov_b32 m0, s37
	s_add_u32 s16, s24, 0x28080
	global_load_lds_dwordx4 v[0:1], off
	v_lshl_add_u64 v[0:1], v[2:3], 0, s[14:15]
	s_mov_b32 m0, s38
	s_addc_u32 s17, s25, 0
	global_load_lds_dwordx4 v[0:1], off
	s_add_i32 m0, s30, 0x1c000
	v_lshl_add_u64 v[0:1], s[16:17], 0, v[168:169]
	global_load_lds_dwordx4 v[0:1], off
	v_lshl_add_u64 v[0:1], s[16:17], 0, v[164:165]
	s_add_i32 m0, s30, 0x1e000
	s_cmpk_lt_u32 s2, 0x100
	global_load_lds_dwordx4 v[0:1], off
	v_lshlrev_b32_e32 v1, 2, v185
	v_lshl_or_b32 v0, v185, 6, v192
	v_and_b32_e32 v1, 32, v1
	v_bitop3_b32 v1, v0, s18, v1 bitop3:0xde
	v_and_b32_e32 v0, 8, v184
	v_readlane_b32 s56, v254, 19
	v_lshl_or_b32 v2, s19, 7, v193
	s_waitcnt vmcnt(6)
	s_cselect_b64 s[16:17], -1, 0
	v_lshlrev_b32_e32 v172, 2, v0
	v_readlane_b32 s66, v254, 29
	v_readlane_b32 s67, v254, 30
	v_add_u16_e32 v3, v187, v188
	s_add_i32 s41, 0, 0x10000
	s_add_i32 s44, 0, 0x14000
	s_add_i32 s46, 0, 0x18000
	s_add_i32 s48, 0, 0x1c000
	v_lshl_add_u64 v[174:175], s[66:67], 0, v[172:173]
	v_lshlrev_b32_e32 v172, 1, v0
	v_lshrrev_b16_e32 v3, 1, v3
	v_add_u32_e32 v200, s41, v2
	v_add_u32_e32 v201, s44, v2
	s_add_i32 s41, s41, s3
	s_add_i32 s44, s44, s3
	v_add_u32_e32 v203, s46, v2
	v_add_u32_e32 v205, s48, v2
	s_add_i32 s46, s46, s3
	s_add_i32 s48, s48, s3
	v_lshl_add_u64 v[176:177], s[0:1], 0, v[172:173]
	v_or_b32_e32 v199, s19, v191
	v_add_lshl_u32 v178, v9, v3, 1
	v_mov_b32_e32 v179, v173
	v_add_lshl_u32 v180, v8, v3, 1
	v_mov_b32_e32 v181, v173
	v_add_u32_e32 v202, 0, v1
	s_add_i32 s39, s30, 0xc000
	s_add_i32 s40, s30, 0xe000
	s_movk_i32 s42, 0x500
	v_lshlrev_b32_e32 v182, 1, v0
	s_add_i32 s43, s41, 0x2000
	s_add_i32 s45, s44, 0x2000
	s_add_i32 s47, s46, 0x2000
	s_add_i32 s49, s48, 0x2000
	v_mov_b32_e32 v206, 0x170
	s_mov_b64 s[18:19], s[22:23]
	s_andn2_b64 vcc, exec, s[10:11]
	s_cbranch_vccnz .Lpe_bar_3
	v_writelane_b32 v255, 1, 53
	s_branch .Lpe_done_3

.Lpe_done_3:
	v_readlane_b32 s57, v254, 20
	v_readlane_b32 s58, v254, 21
	v_readlane_b32 s59, v254, 22
	v_readlane_b32 s60, v254, 23
	v_readlane_b32 s61, v254, 24
	v_readlane_b32 s62, v254, 25
	v_readlane_b32 s63, v254, 26
	v_readlane_b32 s64, v254, 27
	v_readlane_b32 s65, v254, 28
	v_readlane_b32 s68, v254, 31
	v_readlane_b32 s69, v254, 32
	v_readlane_b32 s70, v254, 33
	v_readlane_b32 s71, v254, 34
	s_branch .LBB0_786

.LBB0_801:
	s_lshl_b32 s10, s10, 5
	s_and_b32 s19, s10, 0x60
	s_mov_b64 s[10:11], 0x80
	s_add_i32 m0, s27, 0x18000
	v_lshl_add_u64 v[6:7], v[6:7], 0, s[10:11]
	s_lshl_b32 s18, s15, 13
	s_waitcnt vmcnt(2)
	s_barrier
	global_load_lds_dwordx4 v[6:7], off
	v_lshl_add_u64 v[4:5], v[4:5], 0, s[10:11]
	s_add_i32 m0, s27, 0x1a000
	s_add_i32 s42, s27, 0x8000
	s_add_i32 s43, s27, 0xa000
	global_load_lds_dwordx4 v[4:5], off
	v_lshl_add_u64 v[0:1], v[0:1], 0, s[10:11]
	s_mov_b32 m0, s42
	s_add_u32 s16, s30, 0x20080
	global_load_lds_dwordx4 v[0:1], off
	v_lshl_add_u64 v[0:1], v[2:3], 0, s[10:11]
	s_mov_b32 m0, s43
	s_addc_u32 s17, s31, 0
	global_load_lds_dwordx4 v[0:1], off
	s_add_i32 m0, s27, 0x1c000
	v_lshl_add_u64 v[0:1], s[16:17], 0, v[152:153]
	global_load_lds_dwordx4 v[0:1], off
	v_lshl_add_u64 v[0:1], s[16:17], 0, v[148:149]
	s_add_i32 m0, s27, 0x1e000
	v_lshlrev_b32_e32 v2, 10, v189
	global_load_lds_dwordx4 v[0:1], off
	v_lshlrev_b32_e32 v1, 2, v185
	v_lshl_or_b32 v0, v185, 6, v192
	v_and_b32_e32 v1, 32, v1
	v_bitop3_b32 v0, v0, s18, v1 bitop3:0xde
	v_lshlrev_b32_e32 v1, 7, v204
	v_and_b32_e32 v1, 0x1c000, v1
	v_or3_b32 v1, v187, v1, v2
	s_cmpk_lt_u32 s14, 0x100
	v_add_u32_e32 v156, v1, v188
	v_lshlrev_b32_e32 v1, 3, v190
	v_lshl_or_b32 v172, s15, 6, v185
	v_lshl_or_b32 v173, s19, 7, v193
	s_waitcnt vmcnt(6)
	s_cselect_b64 s[14:15], -1, 0
	v_and_b32_e32 v1, 0x3c000, v1
	s_add_i32 s48, 0, 0x10000
	v_or3_b32 v1, v187, v1, v2
	v_add_u32_e32 v175, s48, v173
	s_add_i32 s50, 0, 0x14000
	s_add_i32 s48, s48, s38
	s_mov_b32 s44, 0
	v_or_b32_e32 v174, s19, v191
	v_mov_b32_e32 v157, v153
	v_add_u32_e32 v158, v1, v188
	v_mov_b32_e32 v159, v153
	v_add_u32_e32 v176, s50, v173
	v_add_u32_e32 v177, 0, v0
	s_movk_i32 s45, 0xc00
	s_add_i32 s46, s27, 0xc000
	s_add_i32 s47, s27, 0xe000
	s_add_i32 s49, s48, 0x2000
	s_add_i32 s50, s50, s38
	s_andn2_b64 vcc, exec, s[2:3]
	s_cbranch_vccnz .Lpe_bar_4
	v_writelane_b32 v255, 1, 53
	s_branch .Lpe_done_4
.Lpe_bar_4:
	s_barrier
.Lpe_done_4:
	s_branch .LBB0_804
.LBB0_802:
	s_mov_b64 s[22:23], 0

.LBB0_883:
	s_mov_b64 s[12:13], 0x80
	s_and_b32 s18, s8, 0x60
	s_add_i32 m0, s25, 0x18000
	v_lshl_add_u64 v[6:7], v[6:7], 0, s[12:13]
	s_lshl_b32 s15, s14, 13
	s_lshl_b32 s19, s18, 7
	s_waitcnt vmcnt(2)
	s_barrier
	global_load_lds_dwordx4 v[6:7], off
	v_lshl_add_u64 v[4:5], v[4:5], 0, s[12:13]
	s_add_i32 m0, s25, 0x1a000
	s_add_i32 s41, s25, 0x8000
	s_add_i32 s42, s25, 0xa000
	global_load_lds_dwordx4 v[4:5], off
	v_lshl_add_u64 v[0:1], v[0:1], 0, s[12:13]
	s_mov_b32 m0, s41
	s_add_u32 s16, s28, 0x20080
	global_load_lds_dwordx4 v[0:1], off
	v_lshl_add_u64 v[0:1], v[2:3], 0, s[12:13]
	s_mov_b32 m0, s42
	s_addc_u32 s17, s29, 0
	global_load_lds_dwordx4 v[0:1], off
	s_add_i32 m0, s25, 0x1c000
	v_lshl_add_u64 v[0:1], s[16:17], 0, v[150:151]
	global_load_lds_dwordx4 v[0:1], off
	v_lshl_add_u64 v[0:1], s[16:17], 0, v[154:155]
	s_add_i32 m0, s25, 0x1e000
	v_lshlrev_b32_e32 v3, 2, v176
	global_load_lds_dwordx4 v[0:1], off
	v_and_b32_e32 v0, 24, v177
	v_lshlrev_b32_e32 v1, 1, v0
	v_lshl_or_b32 v2, v176, 6, v1
	v_or_b32_e32 v1, v1, v181
	v_or_b32_e32 v188, s18, v0
	v_lshlrev_b32_e32 v0, 7, v204
	v_bitop3_b32 v187, s19, v1, v182 bitop3:0xf6
	v_and_b32_e32 v0, 0x1c000, v0
	v_lshlrev_b32_e32 v1, 10, v8
	v_or3_b32 v0, v179, v0, v1
	v_add_u32_e32 v156, v0, v180
	v_lshlrev_b32_e32 v0, 3, v9
	v_and_b32_e32 v3, 32, v3
	s_waitcnt vmcnt(6)
	s_cmpk_lt_u32 s3, 0x100
	v_and_b32_e32 v0, 0x3c000, v0
	v_lshl_or_b32 v186, s14, 6, v176
	v_bitop3_b32 v2, v2, s15, v3 bitop3:0xde
	s_cselect_b64 s[14:15], -1, 0
	v_or3_b32 v0, v179, v0, v1
	s_add_i32 s44, 0, 0x10000
	s_add_i32 s45, 0, 0x14000
	s_sext_i32_i8 s47, s2
	s_waitcnt lgkmcnt(0)
	s_ashr_i32 s43, s9, 31
	v_mov_b32_e32 v157, v151
	v_add_u32_e32 v158, v0, v180
	v_mov_b32_e32 v159, v151
	v_mov_b64_e32 v[160:161], 0x80
	v_mov_b64_e32 v[162:163], 0x7f
	v_add_u32_e32 v189, s44, v187
	v_add_u32_e32 v190, s45, v187
	v_add_u32_e32 v191, 0, v2
	s_movk_i32 s46, 0xc00
	s_andn2_b64 vcc, exec, s[10:11]
	s_cbranch_vccnz .Lpe_bar_5
	v_writelane_b32 v255, 1, 53
	s_branch .Lpe_done_5
.Lpe_bar_5:
	s_barrier
.Lpe_done_5:
	s_branch .LBB0_886
.LBB0_884:
	s_mov_b64 s[2:3], 0

.LBB0_903:
	s_add_u32 s14, s90, 0x1d000000
	s_addc_u32 s15, s91, 0
	s_lshl_b32 s16, s16, 5
	s_and_b32 s21, s16, 0x60
	s_mov_b64 s[16:17], 0x80
	s_add_i32 m0, s37, 0x18000
	v_lshl_add_u64 v[6:7], v[6:7], 0, s[16:17]
	s_lshl_b32 s20, s3, 13
	s_lshl_b32 s22, s21, 7
	s_waitcnt vmcnt(2)
	s_barrier
	global_load_lds_dwordx4 v[6:7], off
	v_lshl_add_u64 v[4:5], v[4:5], 0, s[16:17]
	s_add_i32 m0, s37, 0x1a000
	s_add_i32 s41, s37, 0x8000
	s_add_i32 s42, s37, 0xa000
	global_load_lds_dwordx4 v[4:5], off
	v_lshl_add_u64 v[0:1], v[0:1], 0, s[16:17]
	s_mov_b32 m0, s41
	s_add_u32 s18, s28, 0x60080
	global_load_lds_dwordx4 v[0:1], off
	v_lshl_add_u64 v[0:1], v[2:3], 0, s[16:17]
	s_mov_b32 m0, s42
	s_addc_u32 s19, s29, 0
	global_load_lds_dwordx4 v[0:1], off
	s_add_i32 m0, s37, 0x1c000
	v_lshl_add_u64 v[0:1], s[18:19], 0, v[130:131]
	global_load_lds_dwordx4 v[0:1], off
	v_lshl_add_u64 v[0:1], s[18:19], 0, v[128:129]
	s_add_i32 m0, s37, 0x1e000
	v_lshlrev_b32_e32 v3, 2, v176
	global_load_lds_dwordx4 v[0:1], off
	v_and_b32_e32 v0, 3, v150
	v_lshlrev_b32_e32 v1, 4, v0
	v_lshl_or_b32 v2, v176, 6, v1
	v_and_b32_e32 v3, 32, v3
	v_or_b32_e32 v1, v1, v181
	s_waitcnt vmcnt(6)
	s_cmpk_lt_u32 s2, 0x100
	v_bitop3_b32 v2, v2, s20, v3 bitop3:0xde
	v_bitop3_b32 v152, s22, v1, v182 bitop3:0xf6
	s_cselect_b64 s[18:19], -1, 0
	s_add_i32 s44, 0, 0x10000
	s_add_i32 s45, 0, 0x14000
	v_lshl_or_b32 v151, s3, 6, v176
	s_mov_b32 s43, 0
	v_lshl_or_b32 v153, v0, 2, s21
	v_add3_u32 v132, v9, v179, v180
	v_mov_b32_e32 v133, v131
	v_add3_u32 v134, v8, v179, v180
	v_mov_b32_e32 v135, v131
	v_add_u32_e32 v154, s44, v152
	v_add_u32_e32 v155, s45, v152
	v_add_u32_e32 v156, 0, v2
	s_movk_i32 s46, 0x2600
	s_mov_b32 s47, 0xa0000
	s_mov_b64 s[20:21], 0xb0000
	s_mov_b32 s48, 0xb0000
	s_andn2_b64 vcc, exec, s[10:11]
	s_cbranch_vccnz .Lpe_bar_6
	v_writelane_b32 v255, 1, 53
	s_branch .Lpe_done_6
.Lpe_bar_6:
	s_barrier
.Lpe_done_6:
	s_branch .LBB0_906
.LBB0_904:
	s_mov_b64 s[2:3], 0

.LBB0_989:
	s_add_u32 s10, s90, 0xdd00000
	s_addc_u32 s11, s91, 0
	s_add_u32 s12, s90, 0x7900000
	s_addc_u32 s13, s91, 0
	s_lshl_b32 s5, s5, 5
	s_mov_b64 s[14:15], 0x80
	s_and_b32 s45, s5, 0x60
	s_add_i32 m0, s40, 0x18000
	v_lshl_add_u64 v[6:7], v[6:7], 0, s[14:15]
	s_lshl_b32 s44, s2, 6
	s_lshl_b32 s2, s2, 13
	s_lshl_b32 s5, s45, 7
	s_waitcnt vmcnt(2)
	s_barrier
	global_load_lds_dwordx4 v[6:7], off
	v_lshl_add_u64 v[4:5], v[4:5], 0, s[14:15]
	s_add_i32 m0, s40, 0x1a000
	s_add_i32 s46, s40, 0x8000
	s_add_i32 s47, s40, 0xa000
	global_load_lds_dwordx4 v[4:5], off
	v_lshl_add_u64 v[0:1], v[0:1], 0, s[14:15]
	s_mov_b32 m0, s46
	s_add_u32 s16, s26, 0x60080
	global_load_lds_dwordx4 v[0:1], off
	v_lshl_add_u64 v[0:1], v[2:3], 0, s[14:15]
	s_mov_b32 m0, s47
	s_addc_u32 s17, s27, 0
	global_load_lds_dwordx4 v[0:1], off
	s_add_i32 m0, s40, 0x1c000
	v_lshl_add_u64 v[0:1], s[16:17], 0, v[170:171]
	global_load_lds_dwordx4 v[0:1], off
	v_lshl_add_u64 v[0:1], s[16:17], 0, v[174:175]
	s_add_i32 m0, s40, 0x1e000
	v_bfe_u32 v193, v204, 4, 2
	global_load_lds_dwordx4 v[0:1], off
	v_and_b32_e32 v192, 15, v204
	v_lshlrev_b32_e32 v0, 4, v193
	v_lshlrev_b32_e32 v2, 2, v204
	v_lshl_or_b32 v1, v192, 6, v0
	v_and_b32_e32 v2, 32, v2
	v_bitop3_b32 v3, v1, s2, v2 bitop3:0xde
	v_lshlrev_b32_e32 v1, 6, v204
	s_movk_i32 s2, 0x3c0
	v_and_or_b32 v0, v1, s2, v0
	v_bitop3_b32 v195, s5, v0, v2 bitop3:0xf6
	v_add_u16_e32 v0, v8, v9
	v_lshrrev_b16_e32 v2, 1, v0
	s_sext_i32_i8 s28, s3
	s_mov_b64 s[2:3], 0x60080
	s_waitcnt vmcnt(6)
	v_add_lshl_u32 v0, v10, v2, 1
	v_mov_b32_e32 v1, v171
	s_cmpk_lt_u32 s4, 0x100
	v_lshl_add_u64 v[176:177], v[0:1], 0, s[2:3]
	v_add_lshl_u32 v0, v11, v2, 1
	v_or_b32_e32 v194, s44, v192
	s_cselect_b64 s[16:17], -1, 0
	v_lshl_or_b32 v196, v193, 3, s45
	s_waitcnt lgkmcnt(0)
	s_ashr_i32 s48, s33, 31
	v_lshl_add_u64 v[178:179], v[0:1], 0, s[2:3]
	v_mov_b64_e32 v[180:181], 0x100
	v_mov_b64_e32 v[182:183], 0xff
	s_movk_i32 s49, 0x2600
	s_mov_b64 s[18:19], 0xe00
	s_add_i32 s50, 0, 0x10000
	s_add_i32 s51, 0, 0x14000
	v_add_u32_e32 v197, 0, v3
	s_mov_b64 s[20:21], 0x1e00
	s_movk_i32 s52, 0x1000
	s_mov_b32 s53, 0
	s_andn2_b64 vcc, exec, s[8:9]
	s_cbranch_vccnz .Lpe_bar_7
	v_writelane_b32 v255, 1, 53
	s_branch .Lpe_done_7
.Lpe_bar_7:
	s_barrier
.Lpe_done_7:
	s_branch .LBB0_992
.LBB0_990:
	s_mov_b64 s[2:3], 0

.LBB0_1078:
	s_lshl_b32 s6, s6, 5
	s_and_b32 s12, s6, 0x60
	s_mov_b64 s[6:7], 0x80
	s_add_i32 m0, s28, 0x18000
	v_lshl_add_u64 v[6:7], v[6:7], 0, s[6:7]
	s_lshl_b32 s9, s8, 13
	s_waitcnt vmcnt(2)
	s_barrier
	global_load_lds_dwordx4 v[6:7], off
	v_lshl_add_u64 v[4:5], v[4:5], 0, s[6:7]
	s_add_i32 m0, s28, 0x1a000
	s_add_i32 s40, s28, 0x8000
	s_add_i32 s41, s28, 0xa000
	global_load_lds_dwordx4 v[4:5], off
	v_lshl_add_u64 v[2:3], v[2:3], 0, s[6:7]
	s_mov_b32 m0, s40
	s_add_u32 s10, s22, 0x40080
	global_load_lds_dwordx4 v[2:3], off
	v_lshl_add_u64 v[0:1], v[0:1], 0, s[6:7]
	s_mov_b32 m0, s41
	s_addc_u32 s11, s23, 0
	global_load_lds_dwordx4 v[0:1], off
	s_add_i32 m0, s28, 0x1c000
	v_lshl_add_u64 v[0:1], s[10:11], 0, v[176:177]
	global_load_lds_dwordx4 v[0:1], off
	v_lshl_add_u64 v[0:1], s[10:11], 0, v[178:179]
	s_add_i32 m0, s28, 0x1e000
	v_lshlrev_b32_e32 v2, 11, v10
	global_load_lds_dwordx4 v[0:1], off
	v_lshlrev_b32_e32 v1, 2, v206
	v_lshl_or_b32 v0, v206, 6, v207
	v_and_b32_e32 v1, 32, v1
	v_bitop3_b32 v0, v0, s9, v1 bitop3:0xde
	v_lshlrev_b32_e32 v1, 8, v204
	v_and_b32_e32 v1, 0x38000, v1
	v_or3_b32 v1, v8, v1, v2
	v_add_u32_e32 v182, v1, v9
	v_lshlrev_b32_e32 v1, 4, v11
	s_waitcnt vmcnt(6)
	s_cmpk_lt_u32 s3, 0x100
	v_and_b32_e32 v1, 0x78000, v1
	v_lshl_or_b32 v209, s8, 6, v206
	v_lshl_or_b32 v210, s12, 7, v208
	s_cselect_b64 s[8:9], -1, 0
	v_or3_b32 v1, v8, v1, v2
	s_add_i32 s43, 0, 0x10000
	s_add_i32 s44, 0, 0x14000
	s_sext_i32_i8 s19, s2
	s_waitcnt lgkmcnt(0)
	s_ashr_i32 s42, s33, 31
	v_lshl_or_b32 v211, v205, 2, s12
	v_mov_b32_e32 v183, v181
	v_add_u32_e32 v184, v1, v9
	v_mov_b32_e32 v185, v181
	v_mov_b64_e32 v[186:187], 0x100
	v_mov_b64_e32 v[188:189], 0xff
	v_add_u32_e32 v212, s43, v210
	v_add_u32_e32 v213, s44, v210
	v_add_u32_e32 v214, 0, v0
	s_movk_i32 s45, 0x3fff
	s_movk_i32 s46, 0x3f80
	s_movk_i32 s47, 0x3f70
	s_movk_i32 s48, 0x3f60
	s_movk_i32 s49, 0x3f4f
	s_andn2_b64 vcc, exec, s[0:1]
	s_cbranch_vccnz .Lpe_bar_8
	v_writelane_b32 v255, 1, 53
	s_branch .Lpe_done_8
.Lpe_bar_8:
	s_barrier
.Lpe_done_8:
	s_branch .LBB0_1081
.LBB0_1079:
	s_mov_b64 s[2:3], 0

.LBB0_1233:
	s_add_u32 s6, s90, 0xdd00000
	s_addc_u32 s7, s91, 0
	s_lshl_b32 s8, s8, 5
	s_and_b32 s14, s8, 0x60
	s_mov_b64 s[8:9], 0x80
	s_add_i32 m0, s21, 0x18000
	v_lshl_add_u64 v[6:7], v[6:7], 0, s[8:9]
	s_lshl_b32 s11, s10, 13
	s_lshl_b32 s15, s14, 7
	s_waitcnt vmcnt(2)
	s_barrier
	global_load_lds_dwordx4 v[6:7], off
	v_lshl_add_u64 v[4:5], v[4:5], 0, s[8:9]
	s_add_i32 m0, s21, 0x1a000
	s_add_i32 s40, s21, 0x8000
	s_add_i32 s41, s21, 0xa000
	global_load_lds_dwordx4 v[4:5], off
	v_lshl_add_u64 v[0:1], v[0:1], 0, s[8:9]
	s_mov_b32 m0, s40
	s_add_u32 s12, s24, 0x40080
	global_load_lds_dwordx4 v[0:1], off
	v_lshl_add_u64 v[0:1], v[2:3], 0, s[8:9]
	s_mov_b32 m0, s41
	s_addc_u32 s13, s25, 0
	global_load_lds_dwordx4 v[0:1], off
	s_add_i32 m0, s21, 0x1c000
	v_lshl_add_u64 v[0:1], s[12:13], 0, v[130:131]
	global_load_lds_dwordx4 v[0:1], off
	v_lshl_add_u64 v[0:1], s[12:13], 0, v[134:135]
	s_add_i32 m0, s21, 0x1e000
	s_sext_i32_i8 s46, s2
	global_load_lds_dwordx4 v[0:1], off
	v_and_b32_e32 v0, 15, v204
	v_lshlrev_b32_e32 v1, 1, v11
	v_lshlrev_b32_e32 v2, 2, v204
	v_lshlrev_b32_e32 v3, 6, v204
	s_movk_i32 s2, 0x3c0
	v_lshl_or_b32 v144, s10, 6, v0
	v_lshl_or_b32 v0, v0, 6, v1
	v_and_b32_e32 v2, 32, v2
	v_and_or_b32 v1, v3, s2, v1
	v_bitop3_b32 v145, s15, v1, v2 bitop3:0xf6
	v_lshlrev_b32_e32 v1, 8, v204
	v_bitop3_b32 v0, v0, s11, v2 bitop3:0xde
	v_and_b32_e32 v1, 0x38000, v1
	v_lshlrev_b32_e32 v2, 11, v10
	v_or3_b32 v1, v8, v1, v2
	v_add_u32_e32 v136, v1, v9
	v_lshlrev_b32_e32 v1, 4, v12
	s_waitcnt vmcnt(6)
	s_cmpk_lt_u32 s3, 0x100
	v_and_b32_e32 v1, 0x78000, v1
	s_cselect_b64 s[10:11], -1, 0
	v_or3_b32 v1, v8, v1, v2
	s_add_i32 s43, 0, 0x10000
	s_add_i32 s44, 0, 0x14000
	s_waitcnt lgkmcnt(0)
	s_ashr_i32 s42, s38, 31
	v_or_b32_e32 v146, s14, v11
	v_mov_b32_e32 v137, v131
	v_add_u32_e32 v138, v1, v9
	v_mov_b32_e32 v139, v131
	v_mov_b64_e32 v[140:141], 0x5ac
	v_mov_b64_e32 v[142:143], 0x5ab
	v_add_u32_e32 v147, s43, v145
	v_add_u32_e32 v148, s44, v145
	v_add_u32_e32 v149, 0, v0
	s_movk_i32 s45, 0x1600
	s_andn2_b64 vcc, exec, s[0:1]
	s_cbranch_vccnz .Lpe_bar_9
	v_writelane_b32 v255, 1, 53
	s_branch .Lpe_done_9
.Lpe_bar_9:
	s_barrier
.Lpe_done_9:
	s_branch .LBB0_1236
.LBB0_1234:
	s_mov_b64 s[2:3], 0

.LBB0_1310:
	s_add_u32 s8, s88, 0x4000000
	s_mov_b64 s[10:11], 0x80
	s_addc_u32 s9, s89, 0
	s_lshl_b32 s3, s3, 5
	s_add_i32 m0, s23, 0x18000
	v_lshl_add_u64 v[6:7], v[6:7], 0, s[10:11]
	s_lshl_b32 s13, s2, 13
	s_and_b32 s3, s3, 0x60
	s_waitcnt vmcnt(2)
	s_barrier
	global_load_lds_dwordx4 v[6:7], off
	v_lshl_add_u64 v[4:5], v[4:5], 0, s[10:11]
	s_add_i32 m0, s23, 0x1a000
	s_add_i32 s29, s23, 0x8000
	s_add_i32 s30, s23, 0xa000
	global_load_lds_dwordx4 v[4:5], off
	v_lshl_add_u64 v[2:3], v[2:3], 0, s[10:11]
	s_mov_b32 m0, s29
	s_add_u32 s4, s18, 0xb0080
	global_load_lds_dwordx4 v[2:3], off
	v_lshl_add_u64 v[0:1], v[0:1], 0, s[10:11]
	s_mov_b32 m0, s30
	s_addc_u32 s5, s19, 0
	global_load_lds_dwordx4 v[0:1], off
	s_add_i32 m0, s23, 0x1c000
	v_lshl_add_u64 v[0:1], s[4:5], 0, v[176:177]
	global_load_lds_dwordx4 v[0:1], off
	v_lshl_add_u64 v[0:1], s[4:5], 0, v[178:179]
	s_add_i32 m0, s23, 0x1e000
	s_cmpk_lt_u32 s12, 0x100
	global_load_lds_dwordx4 v[0:1], off
	v_lshlrev_b32_e32 v1, 2, v206
	v_lshl_or_b32 v0, v206, 6, v207
	v_and_b32_e32 v1, 32, v1
	v_bitop3_b32 v0, v0, s13, v1 bitop3:0xde
	s_waitcnt vmcnt(6)
	v_add_u16_e32 v1, v8, v9
	v_lshl_or_b32 v210, s3, 7, v208
	s_cselect_b64 s[12:13], -1, 0
	v_lshrrev_b16_e32 v1, 1, v1
	s_add_i32 s35, 0, 0x10000
	s_add_i32 s40, 0, 0x14000
	v_lshl_or_b32 v209, s2, 6, v206
	s_waitcnt lgkmcnt(0)
	s_ashr_i32 s31, s33, 31
	s_ashr_i32 s34, s80, 31
	v_lshl_or_b32 v211, v205, 2, s3
	v_add_lshl_u32 v182, v10, v1, 1
	v_mov_b32_e32 v183, v181
	v_add_lshl_u32 v184, v11, v1, 1
	v_mov_b32_e32 v185, v181
	v_mov_b64_e32 v[186:187], 0x100
	v_mov_b64_e32 v[188:189], 0xff
	v_add_u32_e32 v212, s35, v210
	v_add_u32_e32 v213, s40, v210
	v_add_u32_e32 v214, 0, v0
	s_movk_i32 s41, 0x3fff
	s_movk_i32 s42, 0x3f80
	s_movk_i32 s43, 0x3f70
	s_movk_i32 s44, 0x3f60
	s_movk_i32 s45, 0x3f4f
	s_andn2_b64 vcc, exec, s[6:7]
	s_cbranch_vccnz .Lpe_bar_10
	v_writelane_b32 v255, 1, 53
	s_branch .Lpe_done_10
.Lpe_bar_10:
	s_barrier
.Lpe_done_10:
	s_branch .LBB0_1313
.LBB0_1311:
	s_mov_b64 s[2:3], 0

.LBB0_1342:
	s_add_u32 s6, s90, 0x1d000000
	s_addc_u32 s7, s91, 0
	s_lshl_b32 s8, s8, 5
	s_and_b32 s17, s8, 0x60
	s_mov_b64 s[8:9], 0x80
	s_add_i32 m0, s42, 0x18000
	v_lshl_add_u64 v[6:7], v[6:7], 0, s[8:9]
	s_lshl_b32 s16, s3, 13
	s_waitcnt vmcnt(2)
	s_barrier
	global_load_lds_dwordx4 v[6:7], off
	v_lshl_add_u64 v[4:5], v[4:5], 0, s[8:9]
	s_add_i32 m0, s42, 0x1a000
	s_add_i32 s47, s42, 0x8000
	s_add_i32 s48, s42, 0xa000
	global_load_lds_dwordx4 v[4:5], off
	v_lshl_add_u64 v[0:1], v[0:1], 0, s[8:9]
	s_mov_b32 m0, s47
	s_add_u32 s10, s12, 0xb0080
	global_load_lds_dwordx4 v[0:1], off
	v_lshl_add_u64 v[0:1], v[2:3], 0, s[8:9]
	s_mov_b32 m0, s48
	s_addc_u32 s11, s13, 0
	global_load_lds_dwordx4 v[0:1], off
	s_add_i32 m0, s42, 0x1c000
	v_lshl_add_u64 v[0:1], s[10:11], 0, v[176:177]
	global_load_lds_dwordx4 v[0:1], off
	v_lshl_add_u64 v[0:1], s[10:11], 0, v[178:179]
	s_add_i32 m0, s42, 0x1e000
	v_lshlrev_b32_e32 v2, 2, v206
	global_load_lds_dwordx4 v[0:1], off
	s_cmpk_lt_u32 s2, 0x100
	v_lshl_or_b32 v1, v206, 6, v207
	v_and_b32_e32 v2, 32, v2
	v_lshl_or_b32 v128, s17, 7, v208
	s_waitcnt vmcnt(6)
	s_cselect_b64 s[10:11], -1, 0
	s_add_i32 s54, 0, 0x10000
	s_add_i32 s56, 0, 0x14000
	v_lshl_or_b32 v0, s3, 6, v206
	v_bitop3_b32 v1, v1, s16, v2 bitop3:0xde
	v_add_u32_e32 v131, s54, v128
	v_add_u32_e32 v132, s56, v128
	s_add_i32 s54, s54, s41
	s_add_i32 s56, s56, s41
	s_add_i32 s58, 0, 0x18000
	v_add_u32_e32 v129, 0xffffc000, v0
	v_lshl_or_b32 v130, v205, 2, s17
	v_add_u32_e32 v133, 0, v1
	s_add_i32 s52, s42, 0xc000
	s_add_i32 s53, s42, 0xe000
	s_add_i32 s55, s54, 0x2000
	s_add_i32 s57, s56, 0x2000
	v_add_u32_e32 v134, s58, v128
	s_andn2_b64 vcc, exec, s[4:5]
	s_cbranch_vccnz .Lpe_bar_11
	v_writelane_b32 v255, 1, 53
	s_branch .Lpe_done_11
.Lpe_bar_11:
	s_barrier
.Lpe_done_11:
	s_branch .LBB0_1345
.LBB0_1343:
	s_mov_b64 s[2:3], 0

.Lpe_bar_12:
	s_barrier
.Lpe_done_12:
	s_branch .LBB0_1480
.LBB0_1478:
	s_mov_b64 s[2:3], 0

.LBB0_1629:
	s_lshl_b32 s4, s4, 5
	s_lshl_b32 s13, s12, 13
	s_and_b32 s16, s4, 0x60
	s_add_u32 s4, s90, 0xa00000
	s_mov_b64 s[6:7], 0x80
	s_addc_u32 s5, s91, 0
	s_add_i32 m0, s43, 0x18000
	v_lshl_add_u64 v[6:7], v[6:7], 0, s[6:7]
	s_waitcnt vmcnt(2)
	s_barrier
	global_load_lds_dwordx4 v[6:7], off
	v_lshl_add_u64 v[4:5], v[4:5], 0, s[6:7]
	s_add_i32 m0, s43, 0x1a000
	s_add_i32 s48, s43, 0x8000
	s_add_i32 s49, s43, 0xa000
	global_load_lds_dwordx4 v[4:5], off
	v_lshl_add_u64 v[0:1], v[0:1], 0, s[6:7]
	s_mov_b32 m0, s48
	s_add_u32 s14, s30, 0x40080
	global_load_lds_dwordx4 v[0:1], off
	v_lshl_add_u64 v[0:1], v[2:3], 0, s[6:7]
	s_mov_b32 m0, s49
	s_addc_u32 s15, s31, 0
	global_load_lds_dwordx4 v[0:1], off
	s_add_i32 m0, s43, 0x1c000
	v_lshl_add_u64 v[0:1], s[14:15], 0, v[136:137]
	global_load_lds_dwordx4 v[0:1], off
	v_lshl_add_u64 v[0:1], s[14:15], 0, v[138:139]
	s_add_i32 m0, s43, 0x1e000
	v_lshlrev_b32_e32 v2, 11, v163
	global_load_lds_dwordx4 v[0:1], off
	v_lshlrev_b32_e32 v1, 2, v166
	v_lshl_or_b32 v0, v166, 6, v167
	v_and_b32_e32 v1, 32, v1
	v_bitop3_b32 v0, v0, s13, v1 bitop3:0xde
	v_lshlrev_b32_e32 v1, 8, v204
	v_and_b32_e32 v1, 0x38000, v1
	v_or3_b32 v1, v147, v1, v2
	v_add_u32_e32 v128, v1, v162
	v_lshlrev_b32_e32 v1, 4, v164
	s_waitcnt vmcnt(6)
	s_cmpk_lt_u32 s11, 0x100
	v_and_b32_e32 v1, 0x78000, v1
	s_sext_i32_i8 s9, s10
	v_lshl_or_b32 v133, s16, 7, v168
	s_cselect_b64 s[10:11], -1, 0
	v_or3_b32 v1, v147, v1, v2
	s_add_i32 s51, 0, 0x10000
	s_add_i32 s52, 0, 0x14000
	v_lshl_or_b32 v132, s12, 6, v166
	s_ashr_i32 s50, s33, 31
	v_lshl_or_b32 v134, v165, 2, s16
	v_mov_b32_e32 v129, v137
	v_add_u32_e32 v130, v1, v162
	v_mov_b32_e32 v131, v137
	v_add_u32_e32 v135, s51, v133
	v_add_u32_e32 v140, s52, v133
	v_add_u32_e32 v141, 0, v0
	s_mov_b32 s53, 0x80000
	s_mov_b64 s[12:13], 0x90000
	s_mov_b32 s54, 0x90000
	s_mov_b64 s[14:15], 0xa0000
	s_mov_b32 s55, 0xa0000
	s_mov_b64 s[16:17], 0xb0000
	s_andn2_b64 vcc, exec, s[2:3]
	s_cbranch_vccnz .Lpe_bar_13
	v_writelane_b32 v255, 1, 53
	s_branch .Lpe_done_13
.Lpe_bar_13:
	s_barrier
.Lpe_done_13:
	s_branch .LBB0_1632
.LBB0_1630:
	s_mov_b64 s[8:9], 0

.Lpe_bar_15:
	s_barrier
.Lpe_done_15:
	s_branch .LBB0_1956
.LBB0_1954:
	s_mov_b64 s[22:23], 0

.LBB0_2035:
	s_mov_b64 s[12:13], 0x80
	s_and_b32 s18, s8, 0x60
	s_add_i32 m0, s25, 0x18000
	v_lshl_add_u64 v[6:7], v[6:7], 0, s[12:13]
	s_lshl_b32 s15, s14, 13
	s_lshl_b32 s19, s18, 7
	s_waitcnt vmcnt(2)
	s_barrier
	global_load_lds_dwordx4 v[6:7], off
	v_lshl_add_u64 v[4:5], v[4:5], 0, s[12:13]
	s_add_i32 m0, s25, 0x1a000
	s_add_i32 s41, s25, 0x8000
	s_add_i32 s42, s25, 0xa000
	global_load_lds_dwordx4 v[4:5], off
	v_lshl_add_u64 v[0:1], v[0:1], 0, s[12:13]
	s_mov_b32 m0, s41
	s_add_u32 s16, s28, 0x20080
	global_load_lds_dwordx4 v[0:1], off
	v_lshl_add_u64 v[0:1], v[2:3], 0, s[12:13]
	s_mov_b32 m0, s42
	s_addc_u32 s17, s29, 0
	global_load_lds_dwordx4 v[0:1], off
	s_add_i32 m0, s25, 0x1c000
	v_lshl_add_u64 v[0:1], s[16:17], 0, v[150:151]
	global_load_lds_dwordx4 v[0:1], off
	v_lshl_add_u64 v[0:1], s[16:17], 0, v[154:155]
	s_add_i32 m0, s25, 0x1e000
	v_lshlrev_b32_e32 v3, 2, v176
	global_load_lds_dwordx4 v[0:1], off
	v_and_b32_e32 v0, 24, v177
	v_lshlrev_b32_e32 v1, 1, v0
	v_lshl_or_b32 v2, v176, 6, v1
	v_or_b32_e32 v1, v1, v181
	v_or_b32_e32 v188, s18, v0
	v_lshlrev_b32_e32 v0, 7, v204
	v_bitop3_b32 v187, s19, v1, v182 bitop3:0xf6
	v_and_b32_e32 v0, 0x1c000, v0
	v_lshlrev_b32_e32 v1, 10, v8
	v_or3_b32 v0, v179, v0, v1
	v_add_u32_e32 v156, v0, v180
	v_lshlrev_b32_e32 v0, 3, v9
	v_and_b32_e32 v3, 32, v3
	s_waitcnt vmcnt(6)
	s_cmpk_lt_u32 s3, 0x100
	v_and_b32_e32 v0, 0x3c000, v0
	v_lshl_or_b32 v186, s14, 6, v176
	v_bitop3_b32 v2, v2, s15, v3 bitop3:0xde
	s_cselect_b64 s[14:15], -1, 0
	v_or3_b32 v0, v179, v0, v1
	s_add_i32 s44, 0, 0x10000
	s_add_i32 s45, 0, 0x14000
	s_sext_i32_i8 s47, s2
	s_ashr_i32 s43, s9, 31
	v_mov_b32_e32 v157, v151
	v_add_u32_e32 v158, v0, v180
	v_mov_b32_e32 v159, v151
	v_mov_b64_e32 v[160:161], 0x80
	v_mov_b64_e32 v[162:163], 0x7f
	v_add_u32_e32 v189, s44, v187
	v_add_u32_e32 v190, s45, v187
	v_add_u32_e32 v191, 0, v2
	s_movk_i32 s46, 0xc00
	s_andn2_b64 vcc, exec, s[10:11]
	s_cbranch_vccnz .Lpe_bar_16
	v_writelane_b32 v255, 1, 53
	s_branch .Lpe_done_16
.Lpe_bar_16:
	s_barrier
.Lpe_done_16:
	s_branch .LBB0_2038
.LBB0_2036:
	s_mov_b64 s[2:3], 0

.LBB0_2055:
	s_add_u32 s14, s90, 0x1d000000
	s_addc_u32 s15, s91, 0
	s_lshl_b32 s16, s16, 5
	s_and_b32 s21, s16, 0x60
	s_mov_b64 s[16:17], 0x80
	s_add_i32 m0, s45, 0x18000
	v_lshl_add_u64 v[6:7], v[6:7], 0, s[16:17]
	s_lshl_b32 s20, s3, 13
	s_lshl_b32 s22, s21, 7
	s_waitcnt vmcnt(2)
	s_barrier
	global_load_lds_dwordx4 v[6:7], off
	v_lshl_add_u64 v[4:5], v[4:5], 0, s[16:17]
	s_add_i32 m0, s45, 0x1a000
	s_add_i32 s49, s45, 0x8000
	s_add_i32 s50, s45, 0xa000
	global_load_lds_dwordx4 v[4:5], off
	v_lshl_add_u64 v[0:1], v[0:1], 0, s[16:17]
	s_mov_b32 m0, s49
	s_add_u32 s18, s38, 0x60080
	global_load_lds_dwordx4 v[0:1], off
	v_lshl_add_u64 v[0:1], v[2:3], 0, s[16:17]
	s_mov_b32 m0, s50
	s_addc_u32 s19, s39, 0
	global_load_lds_dwordx4 v[0:1], off
	s_add_i32 m0, s45, 0x1c000
	v_lshl_add_u64 v[0:1], s[18:19], 0, v[130:131]
	global_load_lds_dwordx4 v[0:1], off
	v_lshl_add_u64 v[0:1], s[18:19], 0, v[128:129]
	s_add_i32 m0, s45, 0x1e000
	v_lshlrev_b32_e32 v3, 2, v176
	global_load_lds_dwordx4 v[0:1], off
	v_and_b32_e32 v0, 3, v150
	v_lshlrev_b32_e32 v1, 4, v0
	v_lshl_or_b32 v2, v176, 6, v1
	v_and_b32_e32 v3, 32, v3
	v_or_b32_e32 v1, v1, v181
	s_waitcnt vmcnt(6)
	s_cmpk_lt_u32 s2, 0x100
	v_bitop3_b32 v2, v2, s20, v3 bitop3:0xde
	v_bitop3_b32 v152, s22, v1, v182 bitop3:0xf6
	s_cselect_b64 s[18:19], -1, 0
	v_lshl_or_b32 v153, v0, 2, s21
	s_add_i32 s52, 0, 0x10000
	s_add_i32 s53, 0, 0x14000
	s_brev_b32 s20, 63
	v_lshl_or_b32 v151, s3, 6, v176
	s_mov_b32 s51, 0
	v_add3_u32 v132, v9, v179, v180
	v_mov_b32_e32 v133, v131
	v_add3_u32 v134, v8, v179, v180
	v_mov_b32_e32 v135, v131
	v_add_u32_e32 v154, s52, v152
	v_add_u32_e32 v155, s53, v152
	v_add_u32_e32 v156, 0, v2
	s_movk_i32 s54, 0x2600
	s_mov_b32 s21, -1
	s_mov_b64 s[22:23], 0x80000
	s_mov_b32 s55, 0x80000
	s_mov_b64 s[24:25], 0x90000
	s_mov_b32 s56, 0x90000
	s_mov_b64 s[26:27], 0xa0000
	s_mov_b32 s57, 0xa0000
	s_mov_b64 s[28:29], 0xb0000
	s_mov_b32 s58, 0xb0000
	s_andn2_b64 vcc, exec, s[10:11]
	s_cbranch_vccnz .Lpe_bar_17
	v_writelane_b32 v255, 1, 53
	s_branch .Lpe_done_17
.Lpe_bar_17:
	s_barrier
.Lpe_done_17:
	s_branch .LBB0_2058
.LBB0_2056:
	s_mov_b64 s[2:3], 0

.Lpe_bar_18:
	s_barrier
.Lpe_done_18:
	s_branch .LBB0_2144
.LBB0_2142:
	s_mov_b64 s[2:3], 0

.LBB0_2230:
	s_add_u32 s6, s88, 0x4000000
	s_addc_u32 s7, s89, 0
	s_lshl_b32 s8, s8, 5
	s_and_b32 s14, s8, 0x60
	s_mov_b64 s[8:9], 0x80
	s_add_i32 m0, s30, 0x18000
	v_lshl_add_u64 v[6:7], v[6:7], 0, s[8:9]
	s_lshl_b32 s11, s10, 13
	s_waitcnt vmcnt(2)
	s_barrier
	global_load_lds_dwordx4 v[6:7], off
	v_lshl_add_u64 v[4:5], v[4:5], 0, s[8:9]
	s_add_i32 m0, s30, 0x1a000
	s_add_i32 s42, s30, 0x8000
	s_add_i32 s43, s30, 0xa000
	global_load_lds_dwordx4 v[4:5], off
	v_lshl_add_u64 v[2:3], v[2:3], 0, s[8:9]
	s_mov_b32 m0, s42
	s_add_u32 s12, s24, 0x40080
	global_load_lds_dwordx4 v[2:3], off
	v_lshl_add_u64 v[0:1], v[0:1], 0, s[8:9]
	s_mov_b32 m0, s43
	s_addc_u32 s13, s25, 0
	global_load_lds_dwordx4 v[0:1], off
	s_add_i32 m0, s30, 0x1c000
	v_lshl_add_u64 v[0:1], s[12:13], 0, v[176:177]
	global_load_lds_dwordx4 v[0:1], off
	v_lshl_add_u64 v[0:1], s[12:13], 0, v[178:179]
	s_add_i32 m0, s30, 0x1e000
	v_lshlrev_b32_e32 v2, 11, v10
	global_load_lds_dwordx4 v[0:1], off
	v_lshlrev_b32_e32 v1, 2, v206
	v_lshl_or_b32 v0, v206, 6, v207
	v_and_b32_e32 v1, 32, v1
	v_bitop3_b32 v0, v0, s11, v1 bitop3:0xde
	v_lshlrev_b32_e32 v1, 8, v204
	v_and_b32_e32 v1, 0x38000, v1
	v_or3_b32 v1, v8, v1, v2
	v_add_u32_e32 v182, v1, v9
	v_lshlrev_b32_e32 v1, 4, v11
	s_waitcnt vmcnt(6)
	s_cmpk_lt_u32 s3, 0x100
	v_and_b32_e32 v1, 0x78000, v1
	v_lshl_or_b32 v209, s10, 6, v206
	v_lshl_or_b32 v210, s14, 7, v208
	s_cselect_b64 s[10:11], -1, 0
	v_or3_b32 v1, v8, v1, v2
	s_add_i32 s45, 0, 0x10000
	s_add_i32 s46, 0, 0x14000
	s_sext_i32_i8 s21, s2
	s_waitcnt lgkmcnt(0)
	s_ashr_i32 s44, s33, 31
	v_lshl_or_b32 v211, v205, 2, s14
	v_mov_b32_e32 v183, v181
	v_add_u32_e32 v184, v1, v9
	v_mov_b32_e32 v185, v181
	v_mov_b64_e32 v[186:187], 0x100
	v_mov_b64_e32 v[188:189], 0xff
	v_add_u32_e32 v212, s45, v210
	v_add_u32_e32 v213, s46, v210
	v_add_u32_e32 v214, 0, v0
	s_movk_i32 s47, 0x3fff
	s_movk_i32 s48, 0x3f80
	s_movk_i32 s49, 0x3f70
	s_movk_i32 s50, 0x3f60
	s_movk_i32 s51, 0x3f4f
	s_andn2_b64 vcc, exec, s[0:1]
	s_cbranch_vccnz .Lpe_bar_19
	v_writelane_b32 v255, 1, 53
	s_branch .Lpe_done_19
.Lpe_bar_19:
	s_barrier
.Lpe_done_19:
	s_branch .LBB0_2233
.LBB0_2231:
	s_mov_b64 s[2:3], 0

.Lpe_bar_20:
	s_barrier
.Lpe_done_20:
	s_branch .LBB0_2388
.LBB0_2386:
	s_mov_b64 s[2:3], 0

.LBB0_2462:
	s_add_u32 s8, s88, 0x4000000
	s_mov_b64 s[10:11], 0x80
	s_addc_u32 s9, s89, 0
	s_lshl_b32 s3, s3, 5
	s_add_i32 m0, s23, 0x18000
	v_lshl_add_u64 v[6:7], v[6:7], 0, s[10:11]
	s_lshl_b32 s13, s2, 13
	s_and_b32 s3, s3, 0x60
	s_waitcnt vmcnt(2)
	s_barrier
	global_load_lds_dwordx4 v[6:7], off
	v_lshl_add_u64 v[4:5], v[4:5], 0, s[10:11]
	s_add_i32 m0, s23, 0x1a000
	s_add_i32 s29, s23, 0x8000
	s_add_i32 s30, s23, 0xa000
	global_load_lds_dwordx4 v[4:5], off
	v_lshl_add_u64 v[2:3], v[2:3], 0, s[10:11]
	s_mov_b32 m0, s29
	s_add_u32 s4, s18, 0xb0080
	global_load_lds_dwordx4 v[2:3], off
	v_lshl_add_u64 v[0:1], v[0:1], 0, s[10:11]
	s_mov_b32 m0, s30
	s_addc_u32 s5, s19, 0
	global_load_lds_dwordx4 v[0:1], off
	s_add_i32 m0, s23, 0x1c000
	v_lshl_add_u64 v[0:1], s[4:5], 0, v[176:177]
	global_load_lds_dwordx4 v[0:1], off
	v_lshl_add_u64 v[0:1], s[4:5], 0, v[178:179]
	s_add_i32 m0, s23, 0x1e000
	s_cmpk_lt_u32 s12, 0x100
	global_load_lds_dwordx4 v[0:1], off
	v_lshlrev_b32_e32 v1, 2, v206
	v_lshl_or_b32 v0, v206, 6, v207
	v_and_b32_e32 v1, 32, v1
	v_bitop3_b32 v0, v0, s13, v1 bitop3:0xde
	s_waitcnt vmcnt(6)
	v_add_u16_e32 v1, v8, v9
	v_lshl_or_b32 v210, s3, 7, v208
	s_cselect_b64 s[12:13], -1, 0
	v_lshrrev_b16_e32 v1, 1, v1
	s_add_i32 s35, 0, 0x10000
	s_add_i32 s36, 0, 0x14000
	v_lshl_or_b32 v209, s2, 6, v206
	s_waitcnt lgkmcnt(0)
	s_ashr_i32 s31, s33, 31
	s_ashr_i32 s34, s80, 31
	v_lshl_or_b32 v211, v205, 2, s3
	v_add_lshl_u32 v182, v10, v1, 1
	v_mov_b32_e32 v183, v181
	v_add_lshl_u32 v184, v11, v1, 1
	v_mov_b32_e32 v185, v181
	v_mov_b64_e32 v[186:187], 0x100
	v_mov_b64_e32 v[188:189], 0xff
	v_add_u32_e32 v212, s35, v210
	v_add_u32_e32 v213, s36, v210
	v_add_u32_e32 v214, 0, v0
	s_movk_i32 s37, 0x3fff
	s_movk_i32 s38, 0x3f80
	s_movk_i32 s39, 0x3f70
	s_movk_i32 s40, 0x3f60
	s_movk_i32 s41, 0x3f4f
	s_andn2_b64 vcc, exec, s[6:7]
	s_cbranch_vccnz .Lpe_bar_21
	v_writelane_b32 v255, 1, 53
	s_branch .Lpe_done_21
.Lpe_bar_21:
	s_barrier
.Lpe_done_21:
	s_branch .LBB0_2465
.LBB0_2463:
	s_mov_b64 s[2:3], 0

.LBB0_2494:
	s_add_u32 s8, s90, 0x1d000000
	s_addc_u32 s9, s91, 0
	s_lshl_b32 s10, s10, 5
	s_and_b32 s17, s10, 0x60
	s_mov_b64 s[10:11], 0x80
	s_add_i32 m0, s50, 0x18000
	v_lshl_add_u64 v[6:7], v[6:7], 0, s[10:11]
	s_lshl_b32 s16, s3, 13
	s_waitcnt vmcnt(2)
	s_barrier
	global_load_lds_dwordx4 v[6:7], off
	v_lshl_add_u64 v[4:5], v[4:5], 0, s[10:11]
	s_add_i32 m0, s50, 0x1a000
	s_add_i32 s55, s50, 0x8000
	s_add_i32 s56, s50, 0xa000
	global_load_lds_dwordx4 v[4:5], off
	v_lshl_add_u64 v[0:1], v[0:1], 0, s[10:11]
	s_mov_b32 m0, s55
	s_add_u32 s12, s14, 0xb0080
	global_load_lds_dwordx4 v[0:1], off
	v_lshl_add_u64 v[0:1], v[2:3], 0, s[10:11]
	s_mov_b32 m0, s56
	s_addc_u32 s13, s15, 0
	global_load_lds_dwordx4 v[0:1], off
	s_add_i32 m0, s50, 0x1c000
	v_lshl_add_u64 v[0:1], s[12:13], 0, v[176:177]
	global_load_lds_dwordx4 v[0:1], off
	v_lshl_add_u64 v[0:1], s[12:13], 0, v[178:179]
	s_add_i32 m0, s50, 0x1e000
	v_lshlrev_b32_e32 v2, 2, v206
	global_load_lds_dwordx4 v[0:1], off
	s_cmpk_lt_u32 s2, 0x100
	v_lshl_or_b32 v1, v206, 6, v207
	v_and_b32_e32 v2, 32, v2
	v_lshl_or_b32 v128, s17, 7, v208
	s_waitcnt vmcnt(6)
	s_cselect_b64 s[12:13], -1, 0
	s_add_i32 s65, 0, 0x10000
	s_add_i32 s67, 0, 0x14000
	v_lshl_or_b32 v0, s3, 6, v206
	v_bitop3_b32 v1, v1, s16, v2 bitop3:0xde
	v_add_u32_e32 v131, s65, v128
	v_add_u32_e32 v132, s67, v128
	s_add_i32 s65, s65, s49
	s_add_i32 s67, s67, s49
	s_add_i32 s69, 0, 0x18000
	v_add_u32_e32 v129, 0xffffc000, v0
	v_lshl_or_b32 v130, v205, 2, s17
	v_add_u32_e32 v133, 0, v1
	s_mov_b64 s[16:17], 0x80000
	s_mov_b32 s60, 0x80000
	s_mov_b64 s[18:19], 0x90000
	s_mov_b32 s61, 0x90000
	s_mov_b64 s[20:21], 0xa0000
	s_mov_b32 s62, 0xa0000
	s_add_i32 s63, s50, 0xc000
	s_add_i32 s64, s50, 0xe000
	s_add_i32 s66, s65, 0x2000
	s_add_i32 s68, s67, 0x2000
	v_add_u32_e32 v134, s69, v128
	s_andn2_b64 vcc, exec, s[6:7]
	s_cbranch_vccnz .Lpe_bar_22
	v_writelane_b32 v255, 1, 53
	s_branch .Lpe_done_22
.Lpe_bar_22:
	s_barrier
.Lpe_done_22:
	s_branch .LBB0_2497
.LBB0_2495:
	s_mov_b64 s[2:3], 0
